# aj1 + nt hint also on the fp16 residual-stream stores (40 stores) of the modulate0 / rowpass loops
# speedup vs baseline: 1.0102x; 1.0022x over previous
.LBB0_207:
	global_load_dwordx4 v[0:3], v84, s[4:5] nt
	global_load_dwordx4 v[4:7], v84, s[4:5] offset:1024 nt
	global_load_dwordx4 v[8:11], v84, s[4:5] offset:2048 nt
	global_load_dwordx4 v[12:15], v84, s[4:5] offset:3072 nt
	global_load_dwordx4 v[16:19], v78, s[4:5] nt
	global_load_dwordx4 v[20:23], v79, s[4:5] nt
	global_load_dwordx4 v[24:27], v80, s[4:5] nt
	global_load_dwordx4 v[28:31], v81, s[4:5] nt
	s_lshl_b64 s[26:27], s[22:23], 12
	v_lshl_add_u64 v[104:105], v[66:67], 0, s[26:27]
	s_waitcnt vmcnt(15)
	v_cvt_pk_f16_f32 v89, v62, v63
	v_cvt_pk_f16_f32 v88, v60, v61
	global_store_dwordx2 v[86:87], v[88:89], off nt
	s_waitcnt vmcnt(15)
	v_cvt_pk_f16_f32 v107, v58, v59
	v_cvt_pk_f16_f32 v106, v56, v57
	global_store_dwordx2 v[86:87], v[106:107], off offset:512 nt
	s_waitcnt vmcnt(15)
	v_cvt_pk_f16_f32 v89, v54, v55
	v_cvt_pk_f16_f32 v88, v52, v53
	global_store_dwordx2 v[86:87], v[88:89], off offset:1024 nt
	s_waitcnt vmcnt(15)
	v_cvt_pk_f16_f32 v107, v50, v51
	v_cvt_pk_f16_f32 v106, v48, v49
	global_store_dwordx2 v[86:87], v[106:107], off offset:1536 nt
	s_waitcnt vmcnt(15)
	v_cvt_pk_f16_f32 v89, v46, v47
	v_cvt_pk_f16_f32 v88, v44, v45
	global_store_dwordx2 v[86:87], v[88:89], off offset:2048 nt
	s_waitcnt vmcnt(15)
	v_cvt_pk_f16_f32 v107, v42, v43
	v_cvt_pk_f16_f32 v106, v40, v41
	global_store_dwordx2 v[86:87], v[106:107], off offset:2560 nt
	s_waitcnt vmcnt(15)
	v_cvt_pk_f16_f32 v89, v38, v39
	v_cvt_pk_f16_f32 v88, v36, v37
	global_store_dwordx2 v[86:87], v[88:89], off offset:3072 nt
	s_waitcnt vmcnt(15)
	v_cvt_pk_f16_f32 v107, v34, v35
	v_cvt_pk_f16_f32 v106, v32, v33
	global_store_dwordx2 v[86:87], v[106:107], off offset:3584 nt
	s_waitcnt vmcnt(15)
	v_cvt_pk_f16_f32 v89, v2, v3
	v_cvt_pk_f16_f32 v88, v0, v1
	global_store_dwordx2 v[104:105], v[88:89], off nt
	s_waitcnt vmcnt(15)
	v_cvt_pk_f16_f32 v107, v6, v7
	v_cvt_pk_f16_f32 v106, v4, v5
	global_store_dwordx2 v[104:105], v[106:107], off offset:512 nt
	s_waitcnt vmcnt(15)
	v_cvt_pk_f16_f32 v89, v10, v11
	v_cvt_pk_f16_f32 v88, v8, v9
	global_store_dwordx2 v[104:105], v[88:89], off offset:1024 nt
	s_waitcnt vmcnt(15)
	v_cvt_pk_f16_f32 v107, v14, v15
	v_cvt_pk_f16_f32 v106, v12, v13
	global_store_dwordx2 v[104:105], v[106:107], off offset:1536 nt
	s_waitcnt vmcnt(15)
	v_cvt_pk_f16_f32 v89, v18, v19
	v_cvt_pk_f16_f32 v88, v16, v17
	global_store_dwordx2 v[104:105], v[88:89], off offset:2048 nt
	s_waitcnt vmcnt(15)
	v_cvt_pk_f16_f32 v107, v22, v23
	v_cvt_pk_f16_f32 v106, v20, v21
	global_store_dwordx2 v[104:105], v[106:107], off offset:2560 nt
	s_waitcnt vmcnt(15)
	v_cvt_pk_f16_f32 v89, v26, v27
	v_cvt_pk_f16_f32 v88, v24, v25
	global_store_dwordx2 v[104:105], v[88:89], off offset:3072 nt
	s_waitcnt vmcnt(15)
	v_cvt_pk_f16_f32 v107, v30, v31
	v_cvt_pk_f16_f32 v106, v28, v29
	global_store_dwordx2 v[104:105], v[106:107], off offset:3584 nt
	s_branch .LBB0_208
.Lmod0_one:
	s_waitcnt vmcnt(7)
	v_cvt_pk_f16_f32 v89, v62, v63
	v_cvt_pk_f16_f32 v88, v60, v61
	global_store_dwordx2 v[86:87], v[88:89], off nt
	s_waitcnt vmcnt(7)
	v_cvt_pk_f16_f32 v107, v58, v59
	v_cvt_pk_f16_f32 v106, v56, v57
	global_store_dwordx2 v[86:87], v[106:107], off offset:512 nt
	s_waitcnt vmcnt(7)
	v_cvt_pk_f16_f32 v89, v54, v55
	v_cvt_pk_f16_f32 v88, v52, v53
	global_store_dwordx2 v[86:87], v[88:89], off offset:1024 nt
	s_waitcnt vmcnt(7)
	v_cvt_pk_f16_f32 v107, v50, v51
	v_cvt_pk_f16_f32 v106, v48, v49
	global_store_dwordx2 v[86:87], v[106:107], off offset:1536 nt
	s_waitcnt vmcnt(7)
	v_cvt_pk_f16_f32 v89, v46, v47
	v_cvt_pk_f16_f32 v88, v44, v45
	global_store_dwordx2 v[86:87], v[88:89], off offset:2048 nt
	s_waitcnt vmcnt(7)
	v_cvt_pk_f16_f32 v107, v42, v43
	v_cvt_pk_f16_f32 v106, v40, v41
	global_store_dwordx2 v[86:87], v[106:107], off offset:2560 nt
	s_waitcnt vmcnt(7)
	v_cvt_pk_f16_f32 v89, v38, v39
	v_cvt_pk_f16_f32 v88, v36, v37
	global_store_dwordx2 v[86:87], v[88:89], off offset:3072 nt
	s_waitcnt vmcnt(7)
	v_cvt_pk_f16_f32 v107, v34, v35
	v_cvt_pk_f16_f32 v106, v32, v33
	global_store_dwordx2 v[86:87], v[106:107], off offset:3584 nt

.LBB0_921:
	s_waitcnt vmcnt(15)
	v_cvt_f32_f16_sdwa v181, v166 dst_sel:DWORD dst_unused:UNUSED_PAD src0_sel:WORD_1
	v_cvt_f32_f16_e32 v180, v166
	s_waitcnt vmcnt(14)
	v_lshlrev_b32_e32 v178, 16, v168
	v_and_b32_e32 v179, 0xffff0000, v168
	v_lshlrev_b32_e32 v168, 16, v169
	v_and_b32_e32 v169, 0xffff0000, v169
	v_cvt_f32_f16_sdwa v183, v167 dst_sel:DWORD dst_unused:UNUSED_PAD src0_sel:WORD_1
	v_cvt_f32_f16_e32 v182, v167
	s_waitcnt lgkmcnt(7)
	v_pk_mul_f32 v[166:167], v[124:125], v[178:179]
	v_pk_mul_f32 v[124:125], v[126:127], v[168:169]
	s_waitcnt vmcnt(10)
	v_cvt_f32_f16_sdwa v169, v164 dst_sel:DWORD dst_unused:UNUSED_PAD src0_sel:WORD_1
	v_cvt_f32_f16_e32 v168, v164
	v_pk_fma_f32 v[126:127], v[180:181], s[30:31], v[166:167] op_sel_hi:[1,0,1]
	v_lshlrev_b32_e32 v166, 16, v162
	v_and_b32_e32 v167, 0xffff0000, v162
	v_lshlrev_b32_e32 v162, 16, v163
	v_and_b32_e32 v163, 0xffff0000, v163
	v_cvt_f32_f16_sdwa v179, v165 dst_sel:DWORD dst_unused:UNUSED_PAD src0_sel:WORD_1
	v_cvt_f32_f16_e32 v178, v165
	s_waitcnt lgkmcnt(6)
	v_pk_mul_f32 v[164:165], v[120:121], v[166:167]
	v_pk_mul_f32 v[120:121], v[122:123], v[162:163]
	v_pk_fma_f32 v[122:123], v[168:169], s[30:31], v[164:165] op_sel_hi:[1,0,1]
	s_waitcnt vmcnt(9)
	v_cvt_f32_f16_sdwa v165, v160 dst_sel:DWORD dst_unused:UNUSED_PAD src0_sel:WORD_1
	v_cvt_f32_f16_e32 v164, v160
	v_lshlrev_b32_e32 v162, 16, v158
	v_and_b32_e32 v163, 0xffff0000, v158
	v_lshlrev_b32_e32 v158, 16, v159
	v_and_b32_e32 v159, 0xffff0000, v159
	v_cvt_f32_f16_sdwa v167, v161 dst_sel:DWORD dst_unused:UNUSED_PAD src0_sel:WORD_1
	v_cvt_f32_f16_e32 v166, v161
	s_waitcnt lgkmcnt(5)
	v_pk_mul_f32 v[160:161], v[116:117], v[162:163]
	v_pk_mul_f32 v[116:117], v[118:119], v[158:159]
	v_pk_fma_f32 v[118:119], v[164:165], s[30:31], v[160:161] op_sel_hi:[1,0,1]
	s_waitcnt vmcnt(8)
	v_cvt_f32_f16_sdwa v161, v154 dst_sel:DWORD dst_unused:UNUSED_PAD src0_sel:WORD_1
	v_cvt_f32_f16_e32 v160, v154
	v_lshlrev_b32_e32 v158, 16, v156
	v_and_b32_e32 v159, 0xffff0000, v156
	v_lshlrev_b32_e32 v156, 16, v157
	v_and_b32_e32 v157, 0xffff0000, v157
	v_cvt_f32_f16_sdwa v163, v155 dst_sel:DWORD dst_unused:UNUSED_PAD src0_sel:WORD_1
	v_cvt_f32_f16_e32 v162, v155
	s_waitcnt lgkmcnt(4)
	v_pk_mul_f32 v[154:155], v[112:113], v[158:159]
	v_pk_mul_f32 v[112:113], v[114:115], v[156:157]
	v_pk_fma_f32 v[114:115], v[160:161], s[30:31], v[154:155] op_sel_hi:[1,0,1]
	s_waitcnt vmcnt(6)
	v_lshlrev_b32_e32 v154, 16, v152
	v_and_b32_e32 v155, 0xffff0000, v152
	v_lshlrev_b32_e32 v152, 16, v153
	v_and_b32_e32 v153, 0xffff0000, v153
	s_waitcnt lgkmcnt(3)
	v_pk_mul_f32 v[110:111], v[110:111], v[152:153]
	s_waitcnt vmcnt(2)
	v_cvt_f32_f16_sdwa v153, v148 dst_sel:DWORD dst_unused:UNUSED_PAD src0_sel:WORD_1
	v_cvt_f32_f16_e32 v152, v148
	v_cvt_f32_f16_sdwa v157, v150 dst_sel:DWORD dst_unused:UNUSED_PAD src0_sel:WORD_1
	v_cvt_f32_f16_sdwa v159, v151 dst_sel:DWORD dst_unused:UNUSED_PAD src0_sel:WORD_1
	v_cvt_f32_f16_e32 v158, v151
	v_cvt_f32_f16_e32 v156, v150
	v_lshlrev_b32_e32 v150, 16, v146
	v_and_b32_e32 v151, 0xffff0000, v146
	v_pk_mul_f32 v[108:109], v[108:109], v[154:155]
	v_lshlrev_b32_e32 v146, 16, v147
	v_and_b32_e32 v147, 0xffff0000, v147
	v_cvt_f32_f16_sdwa v155, v149 dst_sel:DWORD dst_unused:UNUSED_PAD src0_sel:WORD_1
	v_cvt_f32_f16_e32 v154, v149
	s_waitcnt lgkmcnt(2)
	v_pk_mul_f32 v[148:149], v[104:105], v[150:151]
	v_pk_mul_f32 v[104:105], v[106:107], v[146:147]
	v_pk_fma_f32 v[106:107], v[152:153], s[30:31], v[148:149] op_sel_hi:[1,0,1]
	s_waitcnt vmcnt(1)
	v_cvt_f32_f16_sdwa v149, v142 dst_sel:DWORD dst_unused:UNUSED_PAD src0_sel:WORD_1
	v_cvt_f32_f16_e32 v148, v142
	v_lshlrev_b32_e32 v146, 16, v140
	v_and_b32_e32 v147, 0xffff0000, v140
	v_lshlrev_b32_e32 v140, 16, v141
	v_and_b32_e32 v141, 0xffff0000, v141
	v_cvt_f32_f16_sdwa v151, v143 dst_sel:DWORD dst_unused:UNUSED_PAD src0_sel:WORD_1
	v_cvt_f32_f16_e32 v150, v143
	s_waitcnt lgkmcnt(1)
	v_pk_mul_f32 v[142:143], v[100:101], v[146:147]
	v_pk_mul_f32 v[100:101], v[102:103], v[140:141]
	v_lshlrev_b32_e32 v140, 16, v138
	v_and_b32_e32 v141, 0xffff0000, v138
	v_lshlrev_b32_e32 v138, 16, v139
	v_and_b32_e32 v139, 0xffff0000, v139
	v_pk_fma_f32 v[124:125], v[182:183], s[30:31], v[124:125] op_sel_hi:[1,0,1]
	v_pk_fma_f32 v[120:121], v[178:179], s[30:31], v[120:121] op_sel_hi:[1,0,1]
	v_pk_fma_f32 v[102:103], v[148:149], s[30:31], v[142:143] op_sel_hi:[1,0,1]
	s_waitcnt vmcnt(0)
	v_cvt_f32_f16_sdwa v143, v136 dst_sel:DWORD dst_unused:UNUSED_PAD src0_sel:WORD_1
	v_cvt_f32_f16_sdwa v147, v137 dst_sel:DWORD dst_unused:UNUSED_PAD src0_sel:WORD_1
	v_cvt_f32_f16_e32 v146, v137
	v_cvt_f32_f16_e32 v142, v136
	s_waitcnt lgkmcnt(0)
	v_pk_mul_f32 v[98:99], v[98:99], v[138:139]
	v_mov_b32_e32 v136, v126
	v_mov_b32_e32 v137, v122
	v_mov_b32_e32 v138, v127
	v_mov_b32_e32 v139, v123
	v_pk_mul_f32 v[96:97], v[96:97], v[140:141]
	v_pk_add_f32 v[136:137], v[136:137], v[138:139]
	v_mov_b32_e32 v138, v124
	v_mov_b32_e32 v139, v120
	v_mov_b32_e32 v140, v125
	v_mov_b32_e32 v141, v121
	v_pk_fma_f32 v[116:117], v[166:167], s[30:31], v[116:117] op_sel_hi:[1,0,1]
	v_pk_add_f32 v[138:139], v[138:139], v[140:141]
	v_mov_b32_e32 v140, v118
	v_pk_add_f32 v[136:137], v[136:137], v[138:139]
	v_pk_mov_b32 v[138:139], v[118:119], v[116:117] op_sel:[1,0]
	v_mov_b32_e32 v141, v117
	v_pk_add_f32 v[138:139], v[138:139], v[140:141]
	v_pk_fma_f32 v[112:113], v[162:163], s[30:31], v[112:113] op_sel_hi:[1,0,1]
	v_pk_fma_f32 v[110:111], v[158:159], s[30:31], v[110:111] op_sel_hi:[1,0,1]
	v_pk_fma_f32 v[108:109], v[156:157], s[30:31], v[108:109] op_sel_hi:[1,0,1]
	v_add_f32_e32 v136, 0, v136
	v_pk_add_f32 v[138:139], v[138:139], v[138:139] op_sel:[0,1] op_sel_hi:[1,0]
	v_pk_fma_f32 v[96:97], v[142:143], s[30:31], v[96:97] op_sel_hi:[1,0,1]
	v_add_f32_e32 v136, v136, v137
	v_add_f32_e32 v140, v114, v115
	v_add_f32_e32 v142, v112, v113
	v_mov_b32_e32 v137, v108
	v_mov_b32_e32 v139, v109
	v_mov_b32_e32 v141, v110
	v_mov_b32_e32 v143, v111
	v_pk_fma_f32 v[104:105], v[154:155], s[30:31], v[104:105] op_sel_hi:[1,0,1]
	v_pk_add_f32 v[136:137], v[136:137], v[138:139]
	v_pk_add_f32 v[138:139], v[140:141], v[142:143]
	v_mov_b32_e32 v140, v106
	v_pk_add_f32 v[136:137], v[136:137], v[138:139]
	v_pk_mov_b32 v[138:139], v[106:107], v[104:105] op_sel:[1,0]
	v_mov_b32_e32 v141, v105
	v_pk_add_f32 v[138:139], v[138:139], v[140:141]
	v_pk_fma_f32 v[100:101], v[150:151], s[30:31], v[100:101] op_sel_hi:[1,0,1]
	v_pk_fma_f32 v[98:99], v[146:147], s[30:31], v[98:99] op_sel_hi:[1,0,1]
	v_pk_add_f32 v[136:137], v[136:137], v[136:137] op_sel:[0,1] op_sel_hi:[1,0]
	v_pk_add_f32 v[138:139], v[138:139], v[138:139] op_sel:[0,1] op_sel_hi:[1,0]
	v_add_f32_e32 v140, v102, v103
	v_add_f32_e32 v142, v100, v101
	v_mov_b32_e32 v137, v96
	v_mov_b32_e32 v139, v97
	v_mov_b32_e32 v141, v98
	v_mov_b32_e32 v143, v99
	v_pk_add_f32 v[136:137], v[136:137], v[138:139]
	v_pk_add_f32 v[138:139], v[140:141], v[142:143]
	v_lshl_add_u64 v[164:165], v[134:135], 0, s[24:25]
	v_pk_add_f32 v[136:137], v[136:137], v[138:139]
	v_lshl_add_u64 v[168:169], v[134:135], 0, s[28:29]
	v_add_f32_e32 v136, v136, v137
	ds_bpermute_b32 v137, v170, v136
	s_waitcnt lgkmcnt(0)
	v_add_f32_e32 v136, v136, v137
	ds_bpermute_b32 v137, v171, v136
	s_waitcnt lgkmcnt(0)
	v_add_f32_e32 v136, v136, v137
	ds_bpermute_b32 v137, v172, v136
	s_waitcnt lgkmcnt(0)
	v_add_f32_e32 v136, v136, v137
	ds_bpermute_b32 v137, v173, v136
	s_waitcnt lgkmcnt(0)
	v_add_f32_e32 v136, v136, v137
	ds_bpermute_b32 v137, v174, v136
	s_waitcnt lgkmcnt(0)
	v_add_f32_e32 v136, v136, v137
	ds_bpermute_b32 v137, v175, v136
	s_waitcnt lgkmcnt(0)
	v_add_f32_e32 v146, v136, v137
	v_fmamk_f32 v127, v146, 0xba000000, v127
	v_fmamk_f32 v123, v146, 0xba000000, v123
	v_fmamk_f32 v125, v146, 0xba000000, v125
	v_fmac_f32_e32 v126, 0xba000000, v146
	v_fmamk_f32 v121, v146, 0xba000000, v121
	v_fmac_f32_e32 v122, 0xba000000, v146
	v_mov_b32_e32 v138, v127
	v_mov_b32_e32 v139, v123
	v_fmac_f32_e32 v124, 0xba000000, v146
	v_fmac_f32_e32 v120, 0xba000000, v146
	v_mov_b32_e32 v136, v126
	v_mov_b32_e32 v137, v122
	v_pk_mul_f32 v[138:139], v[138:139], v[138:139]
	v_mov_b32_e32 v140, v125
	v_mov_b32_e32 v141, v121
	v_pk_fma_f32 v[136:137], v[136:137], v[136:137], v[138:139]
	v_mov_b32_e32 v138, v124
	v_mov_b32_e32 v139, v120
	v_pk_mul_f32 v[140:141], v[140:141], v[140:141]
	v_fmamk_f32 v119, v146, 0xba000000, v119
	v_pk_fma_f32 v[138:139], v[138:139], v[138:139], v[140:141]
	v_fmac_f32_e32 v118, 0xba000000, v146
	v_pk_add_f32 v[136:137], v[136:137], v[138:139]
	v_fmamk_f32 v117, v146, 0xba000000, v117
	v_fmac_f32_e32 v116, 0xba000000, v146
	v_pk_add_f32 v[136:137], v[136:137], v[136:137] op_sel_hi:[0,1]
	v_pk_mul_f32 v[138:139], v[116:117], v[116:117]
	v_pk_mul_f32 v[140:141], v[118:119], v[118:119]
	v_fmac_f32_e32 v114, 0xba000000, v146
	v_pk_mov_b32 v[142:143], v[140:141], v[138:139] op_sel:[1,0]
	v_mov_b32_e32 v141, v139
	v_fmamk_f32 v115, v146, 0xba000000, v115
	v_fmac_f32_e32 v112, 0xba000000, v146
	v_mul_f32_e32 v136, v114, v114
	v_pk_add_f32 v[138:139], v[142:143], v[140:141]
	v_fmamk_f32 v113, v146, 0xba000000, v113
	v_pk_fma_f32 v[140:141], v[114:115], v[114:115], v[136:137] op_sel_hi:[1,1,0]
	v_mul_f32_e32 v136, v112, v112
	v_pk_add_f32 v[138:139], v[138:139], v[138:139] op_sel_hi:[0,1]
	v_pk_fma_f32 v[142:143], v[112:113], v[112:113], v[136:137] op_sel_hi:[1,1,0]
	v_fmamk_f32 v111, v146, 0xba000000, v111
	v_fmac_f32_e32 v110, 0xba000000, v146
	v_fmamk_f32 v109, v146, 0xba000000, v109
	v_fmac_f32_e32 v108, 0xba000000, v146
	v_mul_f32_e32 v140, v108, v108
	v_mul_f32_e32 v142, v109, v109
	v_mul_f32_e32 v138, v110, v110
	v_mul_f32_e32 v136, v111, v111
	v_pk_add_f32 v[140:141], v[140:141], v[142:143]
	v_pk_add_f32 v[136:137], v[138:139], v[136:137]
	v_fmamk_f32 v107, v146, 0xba000000, v107
	v_pk_add_f32 v[136:137], v[140:141], v[136:137]
	v_fmac_f32_e32 v106, 0xba000000, v146
	v_fmamk_f32 v105, v146, 0xba000000, v105
	v_fmac_f32_e32 v104, 0xba000000, v146
	v_pk_add_f32 v[136:137], v[136:137], v[136:137] op_sel_hi:[0,1]
	v_pk_mul_f32 v[138:139], v[104:105], v[104:105]
	v_pk_mul_f32 v[140:141], v[106:107], v[106:107]
	v_fmac_f32_e32 v102, 0xba000000, v146
	v_pk_mov_b32 v[142:143], v[140:141], v[138:139] op_sel:[1,0]
	v_mov_b32_e32 v141, v139
	v_fmamk_f32 v103, v146, 0xba000000, v103
	v_fmac_f32_e32 v100, 0xba000000, v146
	v_mul_f32_e32 v136, v102, v102
	v_pk_add_f32 v[138:139], v[142:143], v[140:141]
	v_fmamk_f32 v101, v146, 0xba000000, v101
	v_pk_fma_f32 v[140:141], v[102:103], v[102:103], v[136:137] op_sel_hi:[1,1,0]
	v_mul_f32_e32 v136, v100, v100
	v_pk_add_f32 v[138:139], v[138:139], v[138:139] op_sel_hi:[0,1]
	v_pk_fma_f32 v[142:143], v[100:101], v[100:101], v[136:137] op_sel_hi:[1,1,0]
	v_fmamk_f32 v99, v146, 0xba000000, v99
	v_fmac_f32_e32 v98, 0xba000000, v146
	v_fmamk_f32 v97, v146, 0xba000000, v97
	v_fmac_f32_e32 v96, 0xba000000, v146
	v_mul_f32_e32 v140, v96, v96
	v_mul_f32_e32 v142, v97, v97
	v_mul_f32_e32 v138, v98, v98
	v_mul_f32_e32 v136, v99, v99
	v_pk_add_f32 v[140:141], v[140:141], v[142:143]
	v_pk_add_f32 v[136:137], v[138:139], v[136:137]
	s_nop 0
	v_pk_add_f32 v[136:137], v[140:141], v[136:137]
	s_nop 0
	v_add_f32_e32 v136, v136, v137
	ds_bpermute_b32 v137, v170, v136
	s_waitcnt lgkmcnt(0)
	v_add_f32_e32 v136, v136, v137
	ds_bpermute_b32 v137, v171, v136
	s_waitcnt lgkmcnt(0)
	v_add_f32_e32 v136, v136, v137
	ds_bpermute_b32 v137, v172, v136
	s_waitcnt lgkmcnt(0)
	v_add_f32_e32 v136, v136, v137
	ds_bpermute_b32 v137, v173, v136
	s_waitcnt lgkmcnt(0)
	v_add_f32_e32 v136, v136, v137
	ds_bpermute_b32 v137, v174, v136
	s_waitcnt lgkmcnt(0)
	v_add_f32_e32 v136, v136, v137
	ds_bpermute_b32 v137, v175, v136
	s_waitcnt lgkmcnt(0)
	v_add_f32_e32 v136, v136, v137
	v_fmamk_f32 v136, v136, 0x3a000000, v229
	v_mul_f32_e32 v137, 0x4f800000, v136
	v_cmp_gt_f32_e32 vcc, s5, v136
	s_nop 1
	v_cndmask_b32_e32 v136, v136, v137, vcc
	v_sqrt_f32_e32 v137, v136
	s_nop 0
	v_add_u32_e32 v138, -1, v137
	v_fma_f32 v139, -v138, v137, v136
	v_cmp_ge_f32_e64 s[6:7], 0, v139
	v_add_u32_e32 v139, 1, v137
	s_nop 0
	v_cndmask_b32_e64 v138, v137, v138, s[6:7]
	v_fma_f32 v137, -v139, v137, v136
	v_cmp_lt_f32_e64 s[6:7], 0, v137
	s_nop 1
	v_cndmask_b32_e64 v137, v138, v139, s[6:7]
	v_mul_f32_e32 v138, 0x37800000, v137
	v_cndmask_b32_e32 v137, v137, v138, vcc
	v_cmp_class_f32_e32 vcc, v136, v230
	s_nop 1
	v_cndmask_b32_e32 v136, v137, v136, vcc
	v_div_scale_f32 v137, s[6:7], v136, v136, 1.0
	v_rcp_f32_e32 v138, v137
	s_nop 0
	v_fma_f32 v139, -v137, v138, 1.0
	v_fmac_f32_e32 v138, v139, v138
	v_div_scale_f32 v139, vcc, 1.0, v136, 1.0
	v_mul_f32_e32 v140, v139, v138
	v_fma_f32 v141, -v137, v140, v139
	v_fmac_f32_e32 v140, v141, v138
	v_fma_f32 v137, -v137, v140, v139
	v_div_fmas_f32 v137, v137, v138, v140
	v_div_fixup_f32 v136, v137, v136, 1.0
	v_pk_mul_f32 v[138:139], v[124:125], v[136:137] op_sel_hi:[1,0]
	v_pk_mul_f32 v[124:125], v[126:127], v[136:137] op_sel_hi:[1,0]
	v_pk_fma_f32 v[126:127], v[2:3], v[138:139], v[10:11]
	v_pk_mul_f32 v[138:139], v[120:121], v[136:137] op_sel_hi:[1,0]
	v_pk_mul_f32 v[120:121], v[122:123], v[136:137] op_sel_hi:[1,0]
	v_pk_fma_f32 v[122:123], v[6:7], v[138:139], v[14:15]
	v_pk_mul_f32 v[138:139], v[116:117], v[136:137] op_sel_hi:[1,0]
	v_pk_mul_f32 v[116:117], v[118:119], v[136:137] op_sel_hi:[1,0]
	v_pk_fma_f32 v[118:119], v[18:19], v[138:139], v[26:27]
	v_pk_mul_f32 v[138:139], v[112:113], v[136:137] op_sel_hi:[1,0]
	v_pk_mul_f32 v[112:113], v[114:115], v[136:137] op_sel_hi:[1,0]
	v_pk_fma_f32 v[114:115], v[22:23], v[138:139], v[30:31]
	v_pk_mul_f32 v[138:139], v[104:105], v[136:137] op_sel_hi:[1,0]
	v_pk_fma_f32 v[124:125], v[0:1], v[124:125], v[8:9]
	v_pk_fma_f32 v[120:121], v[4:5], v[120:121], v[12:13]
	v_pk_mul_f32 v[104:105], v[106:107], v[136:137] op_sel_hi:[1,0]
	v_pk_fma_f32 v[106:107], v[38:39], v[138:139], v[46:47]
	v_pk_mul_f32 v[138:139], v[100:101], v[136:137] op_sel_hi:[1,0]
	v_pk_mul_f32 v[110:111], v[110:111], v[136:137] op_sel_hi:[1,0]
	v_pk_mul_f32 v[108:109], v[108:109], v[136:137] op_sel_hi:[1,0]
	v_pk_mul_f32 v[100:101], v[102:103], v[136:137] op_sel_hi:[1,0]
	v_pk_fma_f32 v[102:103], v[50:51], v[138:139], v[58:59]
	v_pk_mul_f32 v[98:99], v[98:99], v[136:137] op_sel_hi:[1,0]
	v_pk_mul_f32 v[96:97], v[96:97], v[136:137] op_sel_hi:[1,0]
	v_mov_b32_e32 v136, v120
	v_mov_b32_e32 v137, v124
	v_mov_b32_e32 v138, v121
	v_mov_b32_e32 v139, v125
	v_pk_add_f32 v[136:137], v[136:137], v[138:139]
	v_mov_b32_e32 v138, v122
	v_mov_b32_e32 v139, v126
	v_mov_b32_e32 v140, v123
	v_mov_b32_e32 v141, v127
	v_pk_fma_f32 v[116:117], v[16:17], v[116:117], v[24:25]
	v_pk_add_f32 v[138:139], v[138:139], v[140:141]
	v_mov_b32_e32 v140, v116
	v_pk_add_f32 v[136:137], v[136:137], v[138:139]
	v_pk_mov_b32 v[138:139], v[116:117], v[118:119] op_sel:[1,0]
	v_mov_b32_e32 v141, v119
	v_pk_add_f32 v[138:139], v[138:139], v[140:141]
	v_pk_fma_f32 v[112:113], v[20:21], v[112:113], v[28:29]
	v_pk_fma_f32 v[108:109], v[32:33], v[108:109], v[40:41]
	v_pk_fma_f32 v[110:111], v[34:35], v[110:111], v[42:43]
	v_add_f32_e32 v137, 0, v137
	v_pk_add_f32 v[138:139], v[138:139], v[138:139] op_sel_hi:[0,1]
	v_add_f32_e32 v137, v136, v137
	v_add_f32_e32 v141, v112, v113
	v_add_f32_e32 v143, v114, v115
	v_mov_b32_e32 v140, v108
	v_mov_b32_e32 v142, v109
	v_mov_b32_e32 v138, v110
	v_mov_b32_e32 v136, v111
	v_pk_fma_f32 v[104:105], v[36:37], v[104:105], v[44:45]
	v_pk_add_f32 v[140:141], v[140:141], v[142:143]
	v_pk_add_f32 v[136:137], v[138:139], v[136:137]
	v_pk_mov_b32 v[138:139], v[104:105], v[106:107] op_sel:[1,0]
	v_pk_add_f32 v[136:137], v[140:141], v[136:137]
	v_mov_b32_e32 v140, v104
	v_mov_b32_e32 v141, v107
	v_pk_add_f32 v[138:139], v[138:139], v[140:141]
	v_pk_fma_f32 v[100:101], v[48:49], v[100:101], v[56:57]
	v_pk_fma_f32 v[96:97], v[52:53], v[96:97], v[60:61]
	v_pk_fma_f32 v[98:99], v[54:55], v[98:99], v[62:63]
	v_pk_add_f32 v[136:137], v[136:137], v[136:137] op_sel_hi:[0,1]
	v_pk_add_f32 v[138:139], v[138:139], v[138:139] op_sel_hi:[0,1]
	v_add_f32_e32 v141, v100, v101
	v_add_f32_e32 v143, v102, v103
	v_mov_b32_e32 v140, v96
	v_mov_b32_e32 v142, v97
	v_mov_b32_e32 v138, v98
	v_mov_b32_e32 v136, v99
	v_pk_add_f32 v[140:141], v[140:141], v[142:143]
	v_pk_add_f32 v[136:137], v[138:139], v[136:137]
	v_cvt_pk_f16_f32 v138, v120, v121
	v_pk_add_f32 v[136:137], v[140:141], v[136:137]
	v_cvt_pk_f16_f32 v139, v122, v123
	v_add_f32_e32 v136, v136, v137
	ds_bpermute_b32 v137, v170, v136
	v_cvt_pk_f16_f32 v142, v112, v113
	v_cvt_pk_f16_f32 v143, v114, v115
	v_cvt_pk_f16_f32 v149, v106, v107
	v_cvt_pk_f16_f32 v148, v104, v105
	s_waitcnt lgkmcnt(0)
	v_add_f32_e32 v136, v136, v137
	ds_bpermute_b32 v137, v171, v136
	v_cvt_pk_f16_f32 v153, v98, v99
	v_cvt_pk_f16_f32 v152, v96, v97
	s_waitcnt lgkmcnt(0)
	v_add_f32_e32 v140, v136, v137
	ds_bpermute_b32 v141, v172, v140
	v_cvt_pk_f16_f32 v136, v124, v125
	v_cvt_pk_f16_f32 v137, v126, v127
	s_waitcnt lgkmcnt(0)
	v_add_f32_e32 v146, v140, v141
	ds_bpermute_b32 v147, v173, v146
	v_cvt_pk_f16_f32 v141, v118, v119
	v_cvt_pk_f16_f32 v140, v116, v117
	s_waitcnt lgkmcnt(0)
	v_add_f32_e32 v150, v146, v147
	ds_bpermute_b32 v151, v174, v150
	v_cvt_pk_f16_f32 v147, v110, v111
	v_cvt_pk_f16_f32 v146, v108, v109
	s_waitcnt lgkmcnt(0)
	v_add_f32_e32 v154, v150, v151
	ds_bpermute_b32 v155, v175, v154
	v_cvt_pk_f16_f32 v150, v100, v101
	v_cvt_pk_f16_f32 v151, v102, v103
	s_waitcnt lgkmcnt(0)
	v_add_f32_e32 v162, v154, v155
	v_fmamk_f32 v125, v162, 0xba000000, v125
	v_fmamk_f32 v121, v162, 0xba000000, v121
	v_fmamk_f32 v127, v162, 0xba000000, v127
	v_fmac_f32_e32 v124, 0xba000000, v162
	v_fmamk_f32 v123, v162, 0xba000000, v123
	v_fmac_f32_e32 v120, 0xba000000, v162
	v_mov_b32_e32 v156, v125
	v_mov_b32_e32 v157, v121
	v_fmac_f32_e32 v126, 0xba000000, v162
	v_fmac_f32_e32 v122, 0xba000000, v162
	v_mov_b32_e32 v154, v124
	v_mov_b32_e32 v155, v120
	v_pk_mul_f32 v[156:157], v[156:157], v[156:157]
	v_mov_b32_e32 v158, v127
	v_mov_b32_e32 v159, v123
	v_pk_fma_f32 v[154:155], v[154:155], v[154:155], v[156:157]
	v_mov_b32_e32 v156, v126
	v_mov_b32_e32 v157, v122
	v_pk_mul_f32 v[158:159], v[158:159], v[158:159]
	v_fmamk_f32 v117, v162, 0xba000000, v117
	v_pk_fma_f32 v[156:157], v[156:157], v[156:157], v[158:159]
	v_fmac_f32_e32 v116, 0xba000000, v162
	v_pk_add_f32 v[154:155], v[154:155], v[156:157]
	v_fmamk_f32 v119, v162, 0xba000000, v119
	v_fmac_f32_e32 v118, 0xba000000, v162
	v_pk_add_f32 v[154:155], v[154:155], v[154:155] op_sel_hi:[0,1]
	v_pk_mul_f32 v[156:157], v[118:119], v[118:119]
	v_pk_mul_f32 v[158:159], v[116:117], v[116:117]
	v_fmac_f32_e32 v112, 0xba000000, v162
	v_pk_mov_b32 v[160:161], v[158:159], v[156:157] op_sel:[1,0]
	v_mov_b32_e32 v159, v157
	v_fmamk_f32 v113, v162, 0xba000000, v113
	v_fmac_f32_e32 v114, 0xba000000, v162
	v_mul_f32_e32 v154, v112, v112
	v_pk_add_f32 v[156:157], v[160:161], v[158:159]
	v_fmamk_f32 v115, v162, 0xba000000, v115
	v_pk_fma_f32 v[158:159], v[112:113], v[112:113], v[154:155] op_sel_hi:[1,1,0]
	v_mul_f32_e32 v154, v114, v114
	v_pk_add_f32 v[156:157], v[156:157], v[156:157] op_sel_hi:[0,1]
	v_pk_fma_f32 v[160:161], v[114:115], v[114:115], v[154:155] op_sel_hi:[1,1,0]
	v_fmamk_f32 v111, v162, 0xba000000, v111
	v_fmac_f32_e32 v110, 0xba000000, v162
	v_fmamk_f32 v109, v162, 0xba000000, v109
	v_fmac_f32_e32 v108, 0xba000000, v162
	v_mul_f32_e32 v158, v108, v108
	v_mul_f32_e32 v160, v109, v109
	v_mul_f32_e32 v156, v110, v110
	v_mul_f32_e32 v154, v111, v111
	v_pk_add_f32 v[158:159], v[158:159], v[160:161]
	v_pk_add_f32 v[154:155], v[156:157], v[154:155]
	v_fmamk_f32 v105, v162, 0xba000000, v105
	v_pk_add_f32 v[154:155], v[158:159], v[154:155]
	v_fmac_f32_e32 v104, 0xba000000, v162
	v_fmamk_f32 v107, v162, 0xba000000, v107
	v_fmac_f32_e32 v106, 0xba000000, v162
	v_pk_add_f32 v[154:155], v[154:155], v[154:155] op_sel_hi:[0,1]
	v_pk_mul_f32 v[156:157], v[106:107], v[106:107]
	v_pk_mul_f32 v[158:159], v[104:105], v[104:105]
	v_fmac_f32_e32 v100, 0xba000000, v162
	v_pk_mov_b32 v[160:161], v[158:159], v[156:157] op_sel:[1,0]
	v_mov_b32_e32 v159, v157
	v_fmamk_f32 v101, v162, 0xba000000, v101
	v_fmac_f32_e32 v102, 0xba000000, v162
	v_mul_f32_e32 v154, v100, v100
	v_pk_add_f32 v[156:157], v[160:161], v[158:159]
	v_fmamk_f32 v103, v162, 0xba000000, v103
	v_pk_fma_f32 v[158:159], v[100:101], v[100:101], v[154:155] op_sel_hi:[1,1,0]
	v_mul_f32_e32 v154, v102, v102
	v_pk_add_f32 v[156:157], v[156:157], v[156:157] op_sel_hi:[0,1]
	v_pk_fma_f32 v[160:161], v[102:103], v[102:103], v[154:155] op_sel_hi:[1,1,0]
	v_fmamk_f32 v99, v162, 0xba000000, v99
	v_fmac_f32_e32 v98, 0xba000000, v162
	v_fmamk_f32 v97, v162, 0xba000000, v97
	v_fmac_f32_e32 v96, 0xba000000, v162
	v_mul_f32_e32 v158, v96, v96
	v_mul_f32_e32 v160, v97, v97
	v_mul_f32_e32 v156, v98, v98
	v_mul_f32_e32 v154, v99, v99
	v_pk_add_f32 v[158:159], v[158:159], v[160:161]
	v_pk_add_f32 v[154:155], v[156:157], v[154:155]
	v_lshl_add_u64 v[156:157], v[134:135], 0, s[10:11]
	v_pk_add_f32 v[154:155], v[158:159], v[154:155]
	v_lshl_add_u64 v[160:161], v[134:135], 0, s[20:21]
	v_add_f32_e32 v154, v154, v155
	ds_bpermute_b32 v155, v170, v154
	v_lshl_add_u64 v[162:163], v[134:135], 0, s[22:23]
	s_waitcnt lgkmcnt(0)
	v_add_f32_e32 v154, v154, v155
	ds_bpermute_b32 v155, v171, v154
	s_waitcnt lgkmcnt(0)
	v_add_f32_e32 v154, v154, v155
	ds_bpermute_b32 v155, v172, v154
	s_waitcnt lgkmcnt(0)
	v_add_f32_e32 v158, v154, v155
	ds_bpermute_b32 v159, v173, v158
	v_lshl_add_u64 v[154:155], v[134:135], 0, s[8:9]
	global_store_dwordx2 v[154:155], v[136:137], off nt
	global_store_dwordx2 v[156:157], v[138:139], off nt
	s_waitcnt lgkmcnt(0)
	v_add_f32_e32 v166, v158, v159
	ds_bpermute_b32 v167, v174, v166
	v_lshl_add_u64 v[158:159], v[134:135], 0, s[12:13]
	global_store_dwordx2 v[158:159], v[140:141], off nt
	global_store_dwordx2 v[160:161], v[142:143], off nt
	global_store_dwordx2 v[162:163], v[146:147], off nt
	s_waitcnt lgkmcnt(0)
	v_add_f32_e32 v177, v166, v167
	ds_bpermute_b32 v178, v175, v177
	v_lshl_add_u64 v[166:167], v[134:135], 0, s[26:27]
	global_store_dwordx2 v[164:165], v[148:149], off nt
	global_store_dwordx2 v[166:167], v[150:151], off nt
	global_store_dwordx2 v[168:169], v[152:153], off nt
	s_waitcnt lgkmcnt(0)
	v_add_f32_e32 v136, v177, v178
	v_fmamk_f32 v136, v136, 0x3a000000, v229
	v_mul_f32_e32 v137, 0x4f800000, v136
	v_cmp_gt_f32_e32 vcc, s5, v136
	s_nop 1
	v_cndmask_b32_e32 v136, v136, v137, vcc
	v_sqrt_f32_e32 v137, v136
	s_nop 0
	v_add_u32_e32 v138, -1, v137
	v_fma_f32 v139, -v138, v137, v136
	v_cmp_ge_f32_e64 s[6:7], 0, v139
	v_add_u32_e32 v139, 1, v137
	s_nop 0
	v_cndmask_b32_e64 v138, v137, v138, s[6:7]
	v_fma_f32 v137, -v139, v137, v136
	v_cmp_lt_f32_e64 s[6:7], 0, v137
	s_nop 1
	v_cndmask_b32_e64 v137, v138, v139, s[6:7]
	v_mul_f32_e32 v138, 0x37800000, v137
	v_cndmask_b32_e32 v137, v137, v138, vcc
	v_cmp_class_f32_e32 vcc, v136, v230
	s_nop 1
	v_cndmask_b32_e32 v136, v137, v136, vcc
	v_div_scale_f32 v137, s[6:7], v136, v136, 1.0
	v_rcp_f32_e32 v138, v137
	s_nop 0
	v_fma_f32 v139, -v137, v138, 1.0
	v_fmac_f32_e32 v138, v139, v138
	v_div_scale_f32 v139, vcc, 1.0, v136, 1.0
	v_mul_f32_e32 v140, v139, v138
	v_fma_f32 v141, -v137, v140, v139
	v_fmac_f32_e32 v140, v141, v138
	v_fma_f32 v137, -v137, v140, v139
	v_div_fmas_f32 v137, v137, v138, v140
	ds_read_b128 v[138:141], v144 offset:32768
	ds_read_b128 v[146:149], v144 offset:24576
	v_div_fixup_f32 v136, v137, v136, 1.0
	v_pk_mul_f32 v[142:143], v[124:125], v[136:137] op_sel_hi:[1,0]
	v_pk_mul_f32 v[150:151], v[126:127], v[136:137] op_sel_hi:[1,0]
	s_waitcnt lgkmcnt(1)
	v_pk_add_f32 v[154:155], v[138:139], 1.0 op_sel_hi:[1,0]
	ds_read_b128 v[124:127], v144 offset:33792
	s_waitcnt lgkmcnt(1)
	v_pk_fma_f32 v[142:143], v[154:155], v[142:143], v[146:147]
	v_pk_add_f32 v[152:153], v[140:141], 1.0 op_sel_hi:[1,0]
	ds_read_b128 v[138:141], v144 offset:25600
	v_pk_fma_f32 v[148:149], v[152:153], v[150:151], v[148:149]
	v_cvt_pk_bf16_f32 v142, v142, v143
	v_bfe_u32 v137, v148, 16, 1
	v_add3_u32 v137, v148, v137, s69
	v_lshrrev_b32_e32 v137, 16, v137
	v_pk_mul_f32 v[120:121], v[120:121], v[136:137] op_sel_hi:[1,0]
	s_waitcnt lgkmcnt(1)
	v_pk_add_f32 v[124:125], v[124:125], 1.0 op_sel_hi:[1,0]
	v_pk_mul_f32 v[122:123], v[122:123], v[136:137] op_sel_hi:[1,0]
	s_waitcnt lgkmcnt(0)
	v_pk_fma_f32 v[120:121], v[124:125], v[120:121], v[138:139]
	v_pk_add_f32 v[126:127], v[126:127], 1.0 op_sel_hi:[1,0]
	v_pk_fma_f32 v[122:123], v[126:127], v[122:123], v[140:141]
	v_cvt_pk_bf16_f32 v120, v120, v121
	v_bfe_u32 v143, v149, 16, 1
	v_add3_u32 v143, v149, v143, s69
	v_and_or_b32 v143, v143, s4, v137
	v_cvt_pk_bf16_f32 v121, v122, v123
	global_store_dwordx2 v[134:135], v[142:143], off
	global_store_dwordx2 v[134:135], v[120:121], off offset:512
	ds_read_b128 v[120:123], v144 offset:34816
	ds_read_b128 v[124:127], v144 offset:26624
	v_pk_mul_f32 v[138:139], v[116:117], v[136:137] op_sel_hi:[1,0]
	v_pk_mul_f32 v[140:141], v[118:119], v[136:137] op_sel_hi:[1,0]
	ds_read_b128 v[116:119], v144 offset:35840
	s_waitcnt lgkmcnt(2)
	v_pk_add_f32 v[142:143], v[122:123], 1.0 op_sel_hi:[1,0]
	v_pk_add_f32 v[146:147], v[120:121], 1.0 op_sel_hi:[1,0]
	ds_read_b128 v[120:123], v144 offset:27648
	s_waitcnt lgkmcnt(2)
	v_pk_fma_f32 v[124:125], v[146:147], v[138:139], v[124:125]
	s_waitcnt lgkmcnt(1)
	v_pk_add_f32 v[116:117], v[116:117], 1.0 op_sel_hi:[1,0]
	v_bfe_u32 v137, v124, 16, 1
	v_add3_u32 v124, v124, v137, s69
	v_bfe_u32 v137, v125, 16, 1
	v_pk_mul_f32 v[112:113], v[112:113], v[136:137] op_sel_hi:[1,0]
	v_pk_mul_f32 v[114:115], v[114:115], v[136:137] op_sel_hi:[1,0]
	s_waitcnt lgkmcnt(0)
	v_pk_fma_f32 v[112:113], v[116:117], v[112:113], v[120:121]
	v_pk_add_f32 v[118:119], v[118:119], 1.0 op_sel_hi:[1,0]
	v_pk_fma_f32 v[126:127], v[142:143], v[140:141], v[126:127]
	v_lshrrev_b32_e32 v124, 16, v124
	v_add3_u32 v125, v125, v137, s69
	v_pk_fma_f32 v[114:115], v[118:119], v[114:115], v[122:123]
	v_and_or_b32 v124, v125, s4, v124
	v_cvt_pk_bf16_f32 v112, v112, v113
	v_cvt_pk_bf16_f32 v125, v126, v127
	v_cvt_pk_bf16_f32 v113, v114, v115
	global_store_dwordx2 v[134:135], v[124:125], off offset:1024
	global_store_dwordx2 v[134:135], v[112:113], off offset:1536
	ds_read_b128 v[112:115], v144 offset:36864
	ds_read_b128 v[116:119], v144 offset:28672
	v_pk_mul_f32 v[120:121], v[108:109], v[136:137] op_sel_hi:[1,0]
	v_pk_mul_f32 v[122:123], v[110:111], v[136:137] op_sel_hi:[1,0]
	ds_read_b128 v[108:111], v144 offset:37888
	s_waitcnt lgkmcnt(2)
	v_pk_add_f32 v[124:125], v[114:115], 1.0 op_sel_hi:[1,0]
	v_pk_add_f32 v[126:127], v[112:113], 1.0 op_sel_hi:[1,0]
	ds_read_b128 v[112:115], v144 offset:29696
	v_pk_mul_f32 v[104:105], v[104:105], v[136:137] op_sel_hi:[1,0]
	s_waitcnt lgkmcnt(1)
	v_pk_add_f32 v[108:109], v[108:109], 1.0 op_sel_hi:[1,0]
	v_pk_fma_f32 v[116:117], v[126:127], v[120:121], v[116:117]
	v_pk_mul_f32 v[106:107], v[106:107], v[136:137] op_sel_hi:[1,0]
	s_waitcnt lgkmcnt(0)
	v_pk_fma_f32 v[104:105], v[108:109], v[104:105], v[112:113]
	v_pk_add_f32 v[110:111], v[110:111], 1.0 op_sel_hi:[1,0]
	v_pk_fma_f32 v[118:119], v[124:125], v[122:123], v[118:119]
	v_pk_fma_f32 v[106:107], v[110:111], v[106:107], v[114:115]
	v_cvt_pk_bf16_f32 v116, v116, v117
	v_cvt_pk_bf16_f32 v104, v104, v105
	v_cvt_pk_bf16_f32 v117, v118, v119
	v_cvt_pk_bf16_f32 v105, v106, v107
	global_store_dwordx2 v[134:135], v[116:117], off offset:2048
	global_store_dwordx2 v[134:135], v[104:105], off offset:2560
	ds_read_b128 v[104:107], v144 offset:38912
	ds_read_b128 v[108:111], v144 offset:30720
	v_pk_mul_f32 v[112:113], v[100:101], v[136:137] op_sel_hi:[1,0]
	v_pk_mul_f32 v[114:115], v[102:103], v[136:137] op_sel_hi:[1,0]
	ds_read_b128 v[100:103], v144 offset:39936
	s_waitcnt lgkmcnt(2)
	v_pk_add_f32 v[116:117], v[106:107], 1.0 op_sel_hi:[1,0]
	v_pk_add_f32 v[118:119], v[104:105], 1.0 op_sel_hi:[1,0]
	ds_read_b128 v[104:107], v144 offset:31744
	v_pk_mul_f32 v[96:97], v[96:97], v[136:137] op_sel_hi:[1,0]
	s_waitcnt lgkmcnt(1)
	v_pk_add_f32 v[100:101], v[100:101], 1.0 op_sel_hi:[1,0]
	v_pk_fma_f32 v[108:109], v[118:119], v[112:113], v[108:109]
	v_pk_mul_f32 v[98:99], v[98:99], v[136:137] op_sel_hi:[1,0]
	s_waitcnt lgkmcnt(0)
	v_pk_fma_f32 v[96:97], v[100:101], v[96:97], v[104:105]
	v_pk_add_f32 v[102:103], v[102:103], 1.0 op_sel_hi:[1,0]
	v_pk_fma_f32 v[110:111], v[116:117], v[114:115], v[110:111]
	v_pk_fma_f32 v[98:99], v[102:103], v[98:99], v[106:107]
	v_cvt_pk_bf16_f32 v108, v108, v109
	v_cvt_pk_bf16_f32 v96, v96, v97
	v_cvt_pk_bf16_f32 v109, v110, v111
	v_cvt_pk_bf16_f32 v97, v98, v99
	s_andn2_b64 vcc, exec, s[16:17]
	global_store_dwordx2 v[134:135], v[108:109], off offset:3072
	global_store_dwordx2 v[134:135], v[96:97], off offset:3584
	s_cbranch_vccnz .LBB0_918
	v_mov_b32_e32 v96, v68
	v_mov_b32_e32 v97, v64
	v_mov_b32_e32 v98, v69
	v_mov_b32_e32 v99, v65
	v_pk_add_f32 v[96:97], v[96:97], v[98:99]
	v_mov_b32_e32 v98, v70
	v_mov_b32_e32 v99, v66
	v_mov_b32_e32 v100, v71
	v_mov_b32_e32 v101, v67
	v_pk_add_f32 v[98:99], v[98:99], v[100:101]
	v_mov_b32_e32 v100, v72
	v_pk_add_f32 v[96:97], v[96:97], v[98:99]
	v_mov_b32_e32 v98, v73
	v_mov_b32_e32 v99, v74
	v_mov_b32_e32 v101, v75
	v_pk_add_f32 v[98:99], v[98:99], v[100:101]
	v_add_f32_e32 v97, 0, v97
	v_pk_add_f32 v[98:99], v[98:99], v[98:99] op_sel_hi:[0,1]
	v_add_f32_e32 v97, v96, v97
	v_add_f32_e32 v101, v76, v77
	v_add_f32_e32 v103, v78, v79
	v_mov_b32_e32 v100, v80
	v_mov_b32_e32 v102, v81
	v_mov_b32_e32 v98, v82
	v_mov_b32_e32 v96, v83
	v_pk_add_f32 v[100:101], v[100:101], v[102:103]
	v_pk_add_f32 v[96:97], v[98:99], v[96:97]
	v_mov_b32_e32 v98, v85
	v_pk_add_f32 v[96:97], v[100:101], v[96:97]
	v_mov_b32_e32 v99, v86
	v_mov_b32_e32 v100, v84
	v_mov_b32_e32 v101, v87
	v_pk_add_f32 v[98:99], v[98:99], v[100:101]
	v_pk_add_f32 v[96:97], v[96:97], v[96:97] op_sel_hi:[0,1]
	v_pk_add_f32 v[98:99], v[98:99], v[98:99] op_sel_hi:[0,1]
	v_add_f32_e32 v101, v88, v89
	v_add_f32_e32 v103, v90, v91
	v_mov_b32_e32 v100, v92
	v_mov_b32_e32 v102, v93
	v_mov_b32_e32 v98, v94
	v_mov_b32_e32 v96, v95
	v_pk_add_f32 v[100:101], v[100:101], v[102:103]
	v_pk_add_f32 v[96:97], v[98:99], v[96:97]
	s_ashr_i32 s15, s14, 31
	v_pk_add_f32 v[96:97], v[100:101], v[96:97]
	s_lshl_b64 s[16:17], s[14:15], 12
	v_add_f32_e32 v96, v96, v97
	ds_bpermute_b32 v97, v170, v96
	s_lshr_b32 s14, s14, 12
	s_mulk_i32 s14, 0x6000
	s_waitcnt lgkmcnt(0)
	v_add_f32_e32 v96, v96, v97
	ds_bpermute_b32 v97, v171, v96
	s_waitcnt lgkmcnt(0)
	v_add_f32_e32 v96, v96, v97
	ds_bpermute_b32 v97, v172, v96
	s_waitcnt lgkmcnt(0)
	v_add_f32_e32 v96, v96, v97
	ds_bpermute_b32 v97, v173, v96
	s_waitcnt lgkmcnt(0)
	v_add_f32_e32 v96, v96, v97
	ds_bpermute_b32 v97, v174, v96
	s_waitcnt lgkmcnt(0)
	v_add_f32_e32 v96, v96, v97
	ds_bpermute_b32 v97, v175, v96
	s_waitcnt lgkmcnt(0)
	v_add_f32_e32 v104, v96, v97
	v_fmamk_f32 v65, v104, 0xba000000, v65
	v_fmamk_f32 v69, v104, 0xba000000, v69
	v_fmamk_f32 v67, v104, 0xba000000, v67
	v_fmac_f32_e32 v64, 0xba000000, v104
	v_fmamk_f32 v71, v104, 0xba000000, v71
	v_fmac_f32_e32 v68, 0xba000000, v104
	v_mov_b32_e32 v98, v65
	v_mov_b32_e32 v99, v69
	v_fmamk_f32 v66, v104, 0xba000000, v66
	v_fmamk_f32 v70, v104, 0xba000000, v70
	v_mov_b32_e32 v96, v64
	v_mov_b32_e32 v97, v68
	v_pk_mul_f32 v[98:99], v[98:99], v[98:99]
	v_mov_b32_e32 v100, v67
	v_mov_b32_e32 v101, v71
	v_pk_fma_f32 v[96:97], v[96:97], v[96:97], v[98:99]
	v_mov_b32_e32 v98, v66
	v_mov_b32_e32 v99, v70
	v_pk_mul_f32 v[100:101], v[100:101], v[100:101]
	v_fmamk_f32 v73, v104, 0xba000000, v73
	v_pk_fma_f32 v[98:99], v[98:99], v[98:99], v[100:101]
	v_fmamk_f32 v72, v104, 0xba000000, v72
	v_pk_add_f32 v[96:97], v[96:97], v[98:99]
	v_fmamk_f32 v75, v104, 0xba000000, v75
	v_fmac_f32_e32 v74, 0xba000000, v104
	v_pk_add_f32 v[96:97], v[96:97], v[96:97] op_sel_hi:[0,1]
	v_pk_mul_f32 v[98:99], v[74:75], v[74:75]
	v_pk_mul_f32 v[100:101], v[72:73], v[72:73]
	v_fmamk_f32 v76, v104, 0xba000000, v76
	v_pk_mov_b32 v[102:103], v[100:101], v[98:99] op_sel:[1,0]
	v_mov_b32_e32 v101, v99
	v_fmamk_f32 v77, v104, 0xba000000, v77
	v_fmac_f32_e32 v78, 0xba000000, v104
	v_mul_f32_e32 v96, v76, v76
	v_pk_add_f32 v[98:99], v[102:103], v[100:101]
	v_fmamk_f32 v79, v104, 0xba000000, v79
	v_pk_fma_f32 v[100:101], v[76:77], v[76:77], v[96:97] op_sel_hi:[1,1,0]
	v_mul_f32_e32 v96, v78, v78
	v_pk_add_f32 v[98:99], v[98:99], v[98:99] op_sel_hi:[0,1]
	v_pk_fma_f32 v[102:103], v[78:79], v[78:79], v[96:97] op_sel_hi:[1,1,0]
	v_fmamk_f32 v83, v104, 0xba000000, v83
	v_fmamk_f32 v82, v104, 0xba000000, v82
	v_fmamk_f32 v81, v104, 0xba000000, v81
	v_fmac_f32_e32 v80, 0xba000000, v104
	v_mul_f32_e32 v100, v80, v80
	v_mul_f32_e32 v102, v81, v81
	v_mul_f32_e32 v98, v82, v82
	v_mul_f32_e32 v96, v83, v83
	v_pk_add_f32 v[100:101], v[100:101], v[102:103]
	v_pk_add_f32 v[96:97], v[98:99], v[96:97]
	v_fmamk_f32 v85, v104, 0xba000000, v85
	v_pk_add_f32 v[96:97], v[100:101], v[96:97]
	v_fmamk_f32 v84, v104, 0xba000000, v84
	v_fmamk_f32 v87, v104, 0xba000000, v87
	v_fmac_f32_e32 v86, 0xba000000, v104
	v_pk_add_f32 v[96:97], v[96:97], v[96:97] op_sel_hi:[0,1]
	v_pk_mul_f32 v[98:99], v[86:87], v[86:87]
	v_pk_mul_f32 v[100:101], v[84:85], v[84:85]
	v_fmamk_f32 v88, v104, 0xba000000, v88
	v_pk_mov_b32 v[102:103], v[100:101], v[98:99] op_sel:[1,0]
	v_mov_b32_e32 v101, v99
	v_fmamk_f32 v89, v104, 0xba000000, v89
	v_fmac_f32_e32 v90, 0xba000000, v104
	v_mul_f32_e32 v96, v88, v88
	v_pk_add_f32 v[98:99], v[102:103], v[100:101]
	v_fmamk_f32 v91, v104, 0xba000000, v91
	v_pk_fma_f32 v[100:101], v[88:89], v[88:89], v[96:97] op_sel_hi:[1,1,0]
	v_mul_f32_e32 v96, v90, v90
	v_pk_add_f32 v[98:99], v[98:99], v[98:99] op_sel_hi:[0,1]
	v_pk_fma_f32 v[102:103], v[90:91], v[90:91], v[96:97] op_sel_hi:[1,1,0]
	v_fmamk_f32 v95, v104, 0xba000000, v95
	v_fmamk_f32 v94, v104, 0xba000000, v94
	v_fmamk_f32 v93, v104, 0xba000000, v93
	v_fmac_f32_e32 v92, 0xba000000, v104
	v_mul_f32_e32 v100, v92, v92
	v_mul_f32_e32 v102, v93, v93
	v_mul_f32_e32 v98, v94, v94
	v_mul_f32_e32 v96, v95, v95
	v_pk_add_f32 v[100:101], v[100:101], v[102:103]
	v_pk_add_f32 v[96:97], v[98:99], v[96:97]
	s_nop 0
	v_pk_add_f32 v[96:97], v[100:101], v[96:97]
	s_nop 0
	v_add_f32_e32 v96, v96, v97
	ds_bpermute_b32 v97, v170, v96
	s_waitcnt lgkmcnt(0)
	v_add_f32_e32 v96, v96, v97
	ds_bpermute_b32 v97, v171, v96
	s_waitcnt lgkmcnt(0)
	v_add_f32_e32 v96, v96, v97
	ds_bpermute_b32 v97, v172, v96
	s_waitcnt lgkmcnt(0)
	v_add_f32_e32 v96, v96, v97
	ds_bpermute_b32 v97, v173, v96
	s_waitcnt lgkmcnt(0)
	v_add_f32_e32 v96, v96, v97
	ds_bpermute_b32 v97, v174, v96
	s_waitcnt lgkmcnt(0)
	v_add_f32_e32 v96, v96, v97
	ds_bpermute_b32 v97, v175, v96
	s_waitcnt lgkmcnt(0)
	v_add_f32_e32 v96, v96, v97
	v_fmamk_f32 v96, v96, 0x3a000000, v229
	v_cmp_gt_f32_e32 vcc, s5, v96
	v_mul_f32_e32 v97, 0x4f800000, v96
	s_nop 0
	v_cndmask_b32_e32 v96, v96, v97, vcc
	v_sqrt_f32_e32 v97, v96
	s_nop 0
	v_add_u32_e32 v98, -1, v97
	v_fma_f32 v99, -v98, v97, v96
	v_cmp_ge_f32_e64 s[6:7], 0, v99
	v_add_u32_e32 v99, 1, v97
	s_nop 0
	v_cndmask_b32_e64 v98, v97, v98, s[6:7]
	v_fma_f32 v97, -v99, v97, v96
	v_cmp_lt_f32_e64 s[6:7], 0, v97
	s_nop 1
	v_cndmask_b32_e64 v97, v98, v99, s[6:7]
	v_mul_f32_e32 v98, 0x37800000, v97
	v_cndmask_b32_e32 v97, v97, v98, vcc
	v_cmp_class_f32_e32 vcc, v96, v230
	s_nop 1
	v_cndmask_b32_e32 v96, v97, v96, vcc
	v_div_scale_f32 v97, s[6:7], v96, v96, 1.0
	v_rcp_f32_e32 v98, v97
	s_nop 0
	v_fma_f32 v99, -v97, v98, 1.0
	v_fmac_f32_e32 v98, v99, v98
	v_div_scale_f32 v99, vcc, 1.0, v96, 1.0
	v_mul_f32_e32 v100, v99, v98
	v_fma_f32 v101, -v97, v100, v99
	v_fmac_f32_e32 v100, v101, v98
	v_fma_f32 v97, -v97, v100, v99
	v_div_fmas_f32 v97, v97, v98, v100
	v_div_fixup_f32 v96, v97, v96, 1.0
	v_pk_mul_f32 v[64:65], v[64:65], v[96:97] op_sel_hi:[1,0]
	v_pk_mul_f32 v[66:67], v[66:67], v[96:97] op_sel_hi:[1,0]
	v_pk_fma_f32 v[64:65], v[0:1], v[64:65], v[8:9]
	v_pk_fma_f32 v[66:67], v[2:3], v[66:67], v[10:11]
	v_pk_mul_f32 v[68:69], v[68:69], v[96:97] op_sel_hi:[1,0]
	v_pk_mul_f32 v[70:71], v[70:71], v[96:97] op_sel_hi:[1,0]
	v_cvt_pk_f16_f32 v99, v66, v67
	v_cvt_pk_f16_f32 v98, v64, v65
	v_lshl_add_u64 v[100:101], v[130:131], 0, s[16:17]
	v_pk_fma_f32 v[70:71], v[6:7], v[70:71], v[14:15]
	v_pk_fma_f32 v[68:69], v[4:5], v[68:69], v[12:13]
	v_pk_mul_f32 v[74:75], v[74:75], v[96:97] op_sel_hi:[1,0]
	v_pk_mul_f32 v[72:73], v[72:73], v[96:97] op_sel_hi:[1,0]
	global_store_dwordx2 v[100:101], v[98:99], off nt
	v_cvt_pk_f16_f32 v99, v70, v71
	v_cvt_pk_f16_f32 v98, v68, v69
	v_pk_fma_f32 v[72:73], v[16:17], v[72:73], v[24:25]
	v_pk_fma_f32 v[74:75], v[18:19], v[74:75], v[26:27]
	v_pk_mul_f32 v[78:79], v[78:79], v[96:97] op_sel_hi:[1,0]
	v_pk_mul_f32 v[76:77], v[76:77], v[96:97] op_sel_hi:[1,0]
	global_store_dwordx2 v[100:101], v[98:99], off offset:512 nt
	v_cvt_pk_f16_f32 v99, v74, v75
	v_cvt_pk_f16_f32 v98, v72, v73
	v_pk_fma_f32 v[76:77], v[20:21], v[76:77], v[28:29]
	v_pk_fma_f32 v[78:79], v[22:23], v[78:79], v[30:31]
	v_pk_mul_f32 v[80:81], v[80:81], v[96:97] op_sel_hi:[1,0]
	v_pk_mul_f32 v[82:83], v[82:83], v[96:97] op_sel_hi:[1,0]
	global_store_dwordx2 v[100:101], v[98:99], off offset:1024 nt
	v_cvt_pk_f16_f32 v99, v78, v79
	v_cvt_pk_f16_f32 v98, v76, v77
	v_pk_fma_f32 v[82:83], v[34:35], v[82:83], v[42:43]
	v_pk_fma_f32 v[80:81], v[32:33], v[80:81], v[40:41]
	v_pk_mul_f32 v[86:87], v[86:87], v[96:97] op_sel_hi:[1,0]
	v_pk_mul_f32 v[84:85], v[84:85], v[96:97] op_sel_hi:[1,0]
	global_store_dwordx2 v[100:101], v[98:99], off offset:1536 nt
	v_cvt_pk_f16_f32 v99, v82, v83
	v_cvt_pk_f16_f32 v98, v80, v81
	v_pk_fma_f32 v[84:85], v[36:37], v[84:85], v[44:45]
	v_pk_fma_f32 v[86:87], v[38:39], v[86:87], v[46:47]
	v_pk_mul_f32 v[90:91], v[90:91], v[96:97] op_sel_hi:[1,0]
	v_pk_mul_f32 v[88:89], v[88:89], v[96:97] op_sel_hi:[1,0]
	v_pk_mul_f32 v[92:93], v[92:93], v[96:97] op_sel_hi:[1,0]
	v_pk_mul_f32 v[94:95], v[94:95], v[96:97] op_sel_hi:[1,0]
	global_store_dwordx2 v[100:101], v[98:99], off offset:2048 nt
	v_cvt_pk_f16_f32 v99, v86, v87
	v_cvt_pk_f16_f32 v98, v84, v85
	v_pk_fma_f32 v[88:89], v[48:49], v[88:89], v[56:57]
	v_pk_fma_f32 v[90:91], v[50:51], v[90:91], v[58:59]
	v_pk_fma_f32 v[94:95], v[54:55], v[94:95], v[62:63]
	v_pk_fma_f32 v[92:93], v[52:53], v[92:93], v[60:61]
	global_store_dwordx2 v[100:101], v[98:99], off offset:2560 nt
	v_cvt_pk_f16_f32 v99, v90, v91
	v_cvt_pk_f16_f32 v98, v88, v89
	v_cvt_pk_f16_f32 v97, v94, v95
	v_cvt_pk_f16_f32 v96, v92, v93
	global_store_dwordx2 v[100:101], v[98:99], off offset:3072 nt
	global_store_dwordx2 v[100:101], v[96:97], off offset:3584 nt
	v_mov_b32_e32 v96, v68
	v_mov_b32_e32 v97, v64
	v_mov_b32_e32 v98, v69
	v_mov_b32_e32 v99, v65
	v_pk_add_f32 v[96:97], v[96:97], v[98:99]
	v_mov_b32_e32 v98, v70
	v_mov_b32_e32 v99, v66
	v_mov_b32_e32 v100, v71
	v_mov_b32_e32 v101, v67
	v_pk_add_f32 v[98:99], v[98:99], v[100:101]
	v_mov_b32_e32 v100, v72
	v_pk_add_f32 v[96:97], v[96:97], v[98:99]
	v_pk_mov_b32 v[98:99], v[72:73], v[74:75] op_sel:[1,0]
	v_mov_b32_e32 v101, v75
	v_pk_add_f32 v[98:99], v[98:99], v[100:101]
	v_add_f32_e32 v97, 0, v97
	v_pk_add_f32 v[98:99], v[98:99], v[98:99] op_sel_hi:[0,1]
	v_add_f32_e32 v97, v96, v97
	v_add_f32_e32 v101, v76, v77
	v_add_f32_e32 v103, v78, v79
	v_mov_b32_e32 v100, v80
	v_mov_b32_e32 v102, v81
	v_mov_b32_e32 v98, v82
	v_mov_b32_e32 v96, v83
	v_pk_add_f32 v[100:101], v[100:101], v[102:103]
	v_pk_add_f32 v[96:97], v[98:99], v[96:97]
	v_pk_mov_b32 v[98:99], v[84:85], v[86:87] op_sel:[1,0]
	v_pk_add_f32 v[96:97], v[100:101], v[96:97]
	v_mov_b32_e32 v100, v84
	v_mov_b32_e32 v101, v87
	v_pk_add_f32 v[98:99], v[98:99], v[100:101]
	v_pk_add_f32 v[96:97], v[96:97], v[96:97] op_sel_hi:[0,1]
	v_pk_add_f32 v[98:99], v[98:99], v[98:99] op_sel_hi:[0,1]
	v_add_f32_e32 v101, v88, v89
	v_add_f32_e32 v103, v90, v91
	v_mov_b32_e32 v100, v92
	v_mov_b32_e32 v102, v93
	v_mov_b32_e32 v98, v94
	v_mov_b32_e32 v96, v95
	v_pk_add_f32 v[100:101], v[100:101], v[102:103]
	v_pk_add_f32 v[96:97], v[98:99], v[96:97]
	v_mov_b32_e32 v136, v64
	v_pk_add_f32 v[96:97], v[100:101], v[96:97]
	v_mov_b32_e32 v126, v68
	v_add_f32_e32 v96, v96, v97
	ds_bpermute_b32 v97, v170, v96
	v_mov_b32_e32 v110, v66
	v_mov_b32_e32 v124, v70
	v_mov_b32_e32 v120, v72
	v_mov_b32_e32 v122, v74
	s_waitcnt lgkmcnt(0)
	v_add_f32_e32 v96, v96, v97
	ds_bpermute_b32 v97, v171, v96
	v_mov_b32_e32 v116, v76
	v_mov_b32_e32 v118, v78
	v_mov_b32_e32 v112, v82
	v_mov_b32_e32 v114, v80
	s_waitcnt lgkmcnt(0)
	v_add_f32_e32 v96, v96, v97
	ds_bpermute_b32 v97, v172, v96
	v_mov_b32_e32 v104, v84
	v_mov_b32_e32 v106, v86
	s_waitcnt lgkmcnt(0)
	v_add_f32_e32 v96, v96, v97
	ds_bpermute_b32 v97, v173, v96
	s_waitcnt lgkmcnt(0)
	v_add_f32_e32 v96, v96, v97
	ds_bpermute_b32 v97, v174, v96
	s_waitcnt lgkmcnt(0)
	v_add_f32_e32 v96, v96, v97
	ds_bpermute_b32 v97, v175, v96
	s_waitcnt lgkmcnt(0)
	v_add_f32_e32 v144, v96, v97
	v_fmamk_f32 v137, v144, 0xba000000, v65
	v_fmamk_f32 v127, v144, 0xba000000, v69
	v_fmamk_f32 v111, v144, 0xba000000, v67
	v_fmac_f32_e32 v136, 0xba000000, v144
	v_fmamk_f32 v125, v144, 0xba000000, v71
	v_fmac_f32_e32 v126, 0xba000000, v144
	v_mov_b32_e32 v98, v137
	v_mov_b32_e32 v99, v127
	v_fmac_f32_e32 v110, 0xba000000, v144
	v_fmac_f32_e32 v124, 0xba000000, v144
	v_mov_b32_e32 v96, v136
	v_mov_b32_e32 v97, v126
	v_pk_mul_f32 v[98:99], v[98:99], v[98:99]
	v_mov_b32_e32 v100, v111
	v_mov_b32_e32 v101, v125
	v_pk_fma_f32 v[96:97], v[96:97], v[96:97], v[98:99]
	v_mov_b32_e32 v98, v110
	v_mov_b32_e32 v99, v124
	v_pk_mul_f32 v[100:101], v[100:101], v[100:101]
	v_fmamk_f32 v121, v144, 0xba000000, v73
	v_pk_fma_f32 v[98:99], v[98:99], v[98:99], v[100:101]
	v_fmac_f32_e32 v120, 0xba000000, v144
	v_pk_add_f32 v[96:97], v[96:97], v[98:99]
	v_fmamk_f32 v123, v144, 0xba000000, v75
	v_fmac_f32_e32 v122, 0xba000000, v144
	v_pk_add_f32 v[96:97], v[96:97], v[96:97] op_sel_hi:[0,1]
	v_pk_mul_f32 v[98:99], v[122:123], v[122:123]
	v_pk_mul_f32 v[100:101], v[120:121], v[120:121]
	v_fmac_f32_e32 v116, 0xba000000, v144
	v_pk_mov_b32 v[102:103], v[100:101], v[98:99] op_sel:[1,0]
	v_mov_b32_e32 v101, v99
	v_fmamk_f32 v117, v144, 0xba000000, v77
	v_fmac_f32_e32 v118, 0xba000000, v144
	v_mul_f32_e32 v96, v116, v116
	v_pk_add_f32 v[98:99], v[102:103], v[100:101]
	v_fmamk_f32 v119, v144, 0xba000000, v79
	v_pk_fma_f32 v[100:101], v[116:117], v[116:117], v[96:97] op_sel_hi:[1,1,0]
	v_mul_f32_e32 v96, v118, v118
	v_pk_add_f32 v[98:99], v[98:99], v[98:99] op_sel_hi:[0,1]
	v_pk_fma_f32 v[102:103], v[118:119], v[118:119], v[96:97] op_sel_hi:[1,1,0]
	v_fmamk_f32 v113, v144, 0xba000000, v83
	v_fmac_f32_e32 v112, 0xba000000, v144
	v_fmamk_f32 v115, v144, 0xba000000, v81
	v_fmac_f32_e32 v114, 0xba000000, v144
	v_mul_f32_e32 v100, v114, v114
	v_mul_f32_e32 v102, v115, v115
	v_mul_f32_e32 v98, v112, v112
	v_mul_f32_e32 v96, v113, v113
	v_pk_add_f32 v[100:101], v[100:101], v[102:103]
	v_pk_add_f32 v[96:97], v[98:99], v[96:97]
	v_fmamk_f32 v105, v144, 0xba000000, v85
	v_pk_add_f32 v[96:97], v[100:101], v[96:97]
	v_fmac_f32_e32 v104, 0xba000000, v144
	v_fmamk_f32 v107, v144, 0xba000000, v87
	v_fmac_f32_e32 v106, 0xba000000, v144
	v_pk_add_f32 v[108:109], v[96:97], v[96:97] op_sel_hi:[0,1]
	v_pk_mul_f32 v[96:97], v[106:107], v[106:107]
	v_pk_mul_f32 v[98:99], v[104:105], v[104:105]
	v_mov_b32_e32 v102, v90
	v_pk_mov_b32 v[100:101], v[98:99], v[96:97] op_sel:[1,0]
	v_mov_b32_e32 v99, v97
	v_pk_add_f32 v[96:97], v[100:101], v[98:99]
	v_mov_b32_e32 v100, v88
	v_fmac_f32_e32 v100, 0xba000000, v144
	v_pk_add_f32 v[138:139], v[96:97], v[96:97] op_sel_hi:[0,1]
	v_fmamk_f32 v101, v144, 0xba000000, v89
	v_fmac_f32_e32 v102, 0xba000000, v144
	v_mul_f32_e32 v96, v100, v100
	v_fmamk_f32 v103, v144, 0xba000000, v91
	v_pk_fma_f32 v[140:141], v[100:101], v[100:101], v[96:97] op_sel_hi:[1,1,0]
	v_mul_f32_e32 v96, v102, v102
	v_pk_fma_f32 v[142:143], v[102:103], v[102:103], v[96:97] op_sel_hi:[1,1,0]
	v_mov_b32_e32 v96, v94
	v_mov_b32_e32 v98, v92
	v_fmamk_f32 v97, v144, 0xba000000, v95
	v_fmac_f32_e32 v96, 0xba000000, v144
	v_fmamk_f32 v99, v144, 0xba000000, v93
	v_fmac_f32_e32 v98, 0xba000000, v144
	v_mul_f32_e32 v140, v98, v98
	v_mul_f32_e32 v142, v99, v99
	v_mul_f32_e32 v138, v96, v96
	v_mul_f32_e32 v108, v97, v97
	v_pk_add_f32 v[140:141], v[140:141], v[142:143]
	v_pk_add_f32 v[108:109], v[138:139], v[108:109]
	s_nop 0
	v_pk_add_f32 v[108:109], v[140:141], v[108:109]
	s_nop 0
	v_add_f32_e32 v108, v108, v109
	ds_bpermute_b32 v109, v170, v108
	s_waitcnt lgkmcnt(0)
	v_add_f32_e32 v108, v108, v109
	ds_bpermute_b32 v109, v171, v108
	s_waitcnt lgkmcnt(0)
	v_add_f32_e32 v108, v108, v109
	ds_bpermute_b32 v109, v172, v108
	s_waitcnt lgkmcnt(0)
	v_add_f32_e32 v108, v108, v109
	ds_bpermute_b32 v109, v173, v108
	s_waitcnt lgkmcnt(0)
	v_add_f32_e32 v108, v108, v109
	ds_bpermute_b32 v109, v174, v108
	s_waitcnt lgkmcnt(0)
	v_add_f32_e32 v108, v108, v109
	ds_bpermute_b32 v109, v175, v108
	s_waitcnt lgkmcnt(0)
	v_add_f32_e32 v108, v108, v109
	v_fmamk_f32 v108, v108, 0x3a000000, v229
	v_cmp_gt_f32_e32 vcc, s5, v108
	v_mul_f32_e32 v109, 0x4f800000, v108
	s_nop 0
	v_cndmask_b32_e32 v108, v108, v109, vcc
	v_sqrt_f32_e32 v109, v108
	s_nop 0
	v_add_u32_e32 v138, -1, v109
	v_fma_f32 v139, -v138, v109, v108
	v_cmp_ge_f32_e64 s[6:7], 0, v139
	v_add_u32_e32 v139, 1, v109
	s_nop 0
	v_cndmask_b32_e64 v138, v109, v138, s[6:7]
	v_fma_f32 v109, -v139, v109, v108
	v_cmp_lt_f32_e64 s[6:7], 0, v109
	s_nop 1
	v_cndmask_b32_e64 v109, v138, v139, s[6:7]
	v_mul_f32_e32 v138, 0x37800000, v109
	v_cndmask_b32_e32 v109, v109, v138, vcc
	v_cmp_class_f32_e32 vcc, v108, v230
	s_nop 1
	v_cndmask_b32_e32 v108, v109, v108, vcc
	v_div_scale_f32 v109, s[6:7], v108, v108, 1.0
	v_rcp_f32_e32 v138, v109
	s_nop 0
	v_fma_f32 v139, -v109, v138, 1.0
	v_fmac_f32_e32 v138, v139, v138
	v_div_scale_f32 v139, vcc, 1.0, v108, 1.0
	v_mul_f32_e32 v140, v139, v138
	v_fma_f32 v141, -v109, v140, v139
	v_fmac_f32_e32 v140, v141, v138
	v_fma_f32 v109, -v109, v140, v139
	v_div_fmas_f32 v109, v109, v138, v140
	v_div_fixup_f32 v108, v109, v108, 1.0
	v_add_u32_e32 v109, s14, v176
	ds_read_b128 v[138:141], v109 offset:24576
	ds_read_b128 v[146:149], v109 offset:32768
	v_pk_mul_f32 v[136:137], v[136:137], v[108:109] op_sel_hi:[1,0]
	v_pk_mul_f32 v[110:111], v[110:111], v[108:109] op_sel_hi:[1,0]
	v_pk_mul_f32 v[126:127], v[126:127], v[108:109] op_sel_hi:[1,0]
	v_pk_mul_f32 v[124:125], v[124:125], v[108:109] op_sel_hi:[1,0]
	s_waitcnt lgkmcnt(0)
	v_pk_add_f32 v[146:147], v[146:147], 1.0 op_sel_hi:[1,0]
	v_pk_add_f32 v[142:143], v[148:149], 1.0 op_sel_hi:[1,0]
	v_pk_fma_f32 v[136:137], v[146:147], v[136:137], v[138:139]
	v_pk_fma_f32 v[110:111], v[142:143], v[110:111], v[140:141]
	v_cvt_pk_bf16_f32 v136, v136, v137
	v_cvt_pk_bf16_f32 v137, v110, v111
	v_lshl_add_u64 v[110:111], v[132:133], 0, s[16:17]
	global_store_dwordx2 v[110:111], v[136:137], off
	ds_read_b128 v[136:139], v109 offset:25600
	ds_read_b128 v[140:143], v109 offset:33792
	v_pk_mul_f32 v[120:121], v[120:121], v[108:109] op_sel_hi:[1,0]
	v_pk_mul_f32 v[122:123], v[122:123], v[108:109] op_sel_hi:[1,0]
	v_pk_mul_f32 v[116:117], v[116:117], v[108:109] op_sel_hi:[1,0]
	v_pk_mul_f32 v[118:119], v[118:119], v[108:109] op_sel_hi:[1,0]
	s_waitcnt lgkmcnt(0)
	v_pk_add_f32 v[140:141], v[140:141], 1.0 op_sel_hi:[1,0]
	v_pk_add_f32 v[142:143], v[142:143], 1.0 op_sel_hi:[1,0]
	v_pk_fma_f32 v[126:127], v[140:141], v[126:127], v[136:137]
	v_pk_fma_f32 v[124:125], v[142:143], v[124:125], v[138:139]
	v_cvt_pk_bf16_f32 v126, v126, v127
	v_cvt_pk_bf16_f32 v127, v124, v125
	global_store_dwordx2 v[110:111], v[126:127], off offset:512
	ds_read_b128 v[124:127], v109 offset:26624
	ds_read_b128 v[136:139], v109 offset:34816
	v_pk_mul_f32 v[114:115], v[114:115], v[108:109] op_sel_hi:[1,0]
	v_pk_mul_f32 v[112:113], v[112:113], v[108:109] op_sel_hi:[1,0]
	v_pk_mul_f32 v[104:105], v[104:105], v[108:109] op_sel_hi:[1,0]
	v_pk_mul_f32 v[106:107], v[106:107], v[108:109] op_sel_hi:[1,0]
	s_waitcnt lgkmcnt(0)
	v_pk_add_f32 v[136:137], v[136:137], 1.0 op_sel_hi:[1,0]
	v_pk_add_f32 v[138:139], v[138:139], 1.0 op_sel_hi:[1,0]
	v_pk_fma_f32 v[120:121], v[136:137], v[120:121], v[124:125]
	v_pk_fma_f32 v[122:123], v[138:139], v[122:123], v[126:127]
	v_cvt_pk_bf16_f32 v120, v120, v121
	v_cvt_pk_bf16_f32 v121, v122, v123
	global_store_dwordx2 v[110:111], v[120:121], off offset:1024
	ds_read_b128 v[120:123], v109 offset:27648
	ds_read_b128 v[124:127], v109 offset:35840
	v_pk_mul_f32 v[100:101], v[100:101], v[108:109] op_sel_hi:[1,0]
	v_pk_mul_f32 v[102:103], v[102:103], v[108:109] op_sel_hi:[1,0]
	v_pk_mul_f32 v[98:99], v[98:99], v[108:109] op_sel_hi:[1,0]
	v_pk_mul_f32 v[96:97], v[96:97], v[108:109] op_sel_hi:[1,0]
	s_waitcnt lgkmcnt(0)
	v_pk_add_f32 v[124:125], v[124:125], 1.0 op_sel_hi:[1,0]
	v_pk_add_f32 v[126:127], v[126:127], 1.0 op_sel_hi:[1,0]
	v_pk_fma_f32 v[116:117], v[124:125], v[116:117], v[120:121]
	v_pk_fma_f32 v[118:119], v[126:127], v[118:119], v[122:123]
	v_cvt_pk_bf16_f32 v116, v116, v117
	v_cvt_pk_bf16_f32 v117, v118, v119
	global_store_dwordx2 v[110:111], v[116:117], off offset:1536
	ds_read_b128 v[116:119], v109 offset:28672
	ds_read_b128 v[120:123], v109 offset:36864
	s_waitcnt lgkmcnt(0)
	v_pk_add_f32 v[120:121], v[120:121], 1.0 op_sel_hi:[1,0]
	s_nop 0
	v_pk_fma_f32 v[114:115], v[120:121], v[114:115], v[116:117]
	v_pk_add_f32 v[122:123], v[122:123], 1.0 op_sel_hi:[1,0]
	v_pk_fma_f32 v[112:113], v[122:123], v[112:113], v[118:119]
	v_cvt_pk_bf16_f32 v114, v114, v115
	v_cvt_pk_bf16_f32 v115, v112, v113
	global_store_dwordx2 v[110:111], v[114:115], off offset:2048
	ds_read_b128 v[112:115], v109 offset:29696
	ds_read_b128 v[116:119], v109 offset:37888
	s_waitcnt lgkmcnt(0)
	v_pk_add_f32 v[116:117], v[116:117], 1.0 op_sel_hi:[1,0]
	s_nop 0
	v_pk_fma_f32 v[104:105], v[116:117], v[104:105], v[112:113]
	v_pk_add_f32 v[118:119], v[118:119], 1.0 op_sel_hi:[1,0]
	v_pk_fma_f32 v[106:107], v[118:119], v[106:107], v[114:115]
	v_cvt_pk_bf16_f32 v104, v104, v105
	v_cvt_pk_bf16_f32 v105, v106, v107
	global_store_dwordx2 v[110:111], v[104:105], off offset:2560
	ds_read_b128 v[104:107], v109 offset:30720
	ds_read_b128 v[112:115], v109 offset:38912
	s_waitcnt lgkmcnt(0)
	v_pk_add_f32 v[112:113], v[112:113], 1.0 op_sel_hi:[1,0]
	s_nop 0
	v_pk_fma_f32 v[100:101], v[112:113], v[100:101], v[104:105]
	v_pk_add_f32 v[114:115], v[114:115], 1.0 op_sel_hi:[1,0]
	v_pk_fma_f32 v[102:103], v[114:115], v[102:103], v[106:107]
	v_cvt_pk_bf16_f32 v100, v100, v101
	v_cvt_pk_bf16_f32 v101, v102, v103
	global_store_dwordx2 v[110:111], v[100:101], off offset:3072
	ds_read_b128 v[100:103], v109 offset:31744
	ds_read_b128 v[104:107], v109 offset:39936
	s_waitcnt lgkmcnt(0)
	v_pk_add_f32 v[104:105], v[104:105], 1.0 op_sel_hi:[1,0]
	s_nop 0
	v_pk_fma_f32 v[98:99], v[104:105], v[98:99], v[100:101]
	v_pk_add_f32 v[106:107], v[106:107], 1.0 op_sel_hi:[1,0]
	v_pk_fma_f32 v[96:97], v[106:107], v[96:97], v[102:103]
	v_cvt_pk_bf16_f32 v98, v98, v99
	v_cvt_pk_bf16_f32 v99, v96, v97
	global_store_dwordx2 v[110:111], v[98:99], off offset:3584
	s_branch .LBB0_918
